# gla_pass2: backward-direction chunk outputs exchanged through LDS and normalised per chunk; the OB global round trip and the separate final-norm loop are gone
# speedup vs baseline: 1.0132x; 1.0068x over previous
; #define LAS __attribute__((address_space(3)))
; template <bool OUT>
; __device__ __forceinline__ void gla_chunks(const Params& p, int l, const bf16_t* proj, LAS unsigned char* lds, int seg, int h, int dir, f32x4 (&Sacc)[4], float* outbuf, float& alog) {
;     ...
;                 u32x2 pw; pw.x = cvt_pk_bf16(a[0], a[1]); pw.y = cvt_pk_bf16(a[2], a[3]);
;                 *(LAS u32x2*)(PP + (it * 16 + fr) * GP + jt * 16 + 4 * g) = pw; }
;             __syncthreads();
;         }
;         bf16x8 bv[2];
; #pragma unroll
;         for (int ks = 0; ks < 2; ++ks) bv[ks] = *(const LAS bf16x8*)(VT + (16 * wv + fr) * GP + 32 * ks + 8 * g);
;         if (OUT) {
;             bf16x8 bs[2];
; #pragma unroll
;             for (int m = 0; m < 2; ++m) { u32x4 sw; sw.x = cvt_pk_bf16_mfma(Sacc[2 * m][0], Sacc[2 * m][1]); sw.y = cvt_pk_bf16_mfma(Sacc[2 * m][2], Sacc[2 * m][3]); sw.z = cvt_pk_bf16_mfma(Sacc[2 * m + 1][0], Sacc[2 * m + 1][1]); sw.w = cvt_pk_bf16_mfma(Sacc[2 * m + 1][2], Sacc[2 * m + 1][3]); bs[m] = __builtin_bit_cast(bf16x8, sw); }
; #pragma unroll
;             for (int it = 0; it < 4; ++it) { f32x4 o = {0.f, 0.f, 0.f, 0.f};
; #pragma unroll
;                 for (int ks = 0; ks < 2; ++ks) { const bf16x8 pf = *(const LAS bf16x8*)(PP + (it * 16 + fr) * GP + 32 * ks + 8 * g); o = __builtin_amdgcn_mfma_f32_16x16x32_bf16(pf, bv[ks], o, 0, 0, 0); }
; #pragma unroll
;                 for (int m = 0; m < 2; ++m) { const LAS bf16_t* qp = QT + (it * 16 + fr) * GP + 32 * m + 4 * g; const u32x2 lo = *(const LAS u32x2*)qp, hi = *(const LAS u32x2*)(qp + 16);
;                     u32x4 qw; qw.x = lo.x; qw.y = lo.y; qw.z = hi.x; qw.w = hi.y; o = __builtin_amdgcn_mfma_f32_16x16x32_bf16(__builtin_bit_cast(bf16x8, qw), bs[m], o, 0, 0, 0); }
; #pragma unroll
;                 for (int r = 0; r < 4; ++r) { const int i = it * 16 + 4 * g + r, t = dir ? t0 + 63 - i : t0 + i; outbuf[(size_t)t * 512 + h * 128 + 16 * wv + fr] = o[r]; } }
;         }
; #pragma unroll
;         for (int dt = 0; dt < 4; ++dt) { const f32x4 eb = *(const LAS f32x4*)(EBL + dt * 16 + 4 * g); f32x4 a = Sacc[dt] * eb;
; #pragma unroll
;             for (int ks = 0; ks < 2; ++ks) { const bf16x8 kf = *(const LAS bf16x8*)(KH + (dt * 16 + fr) * GP + 32 * ks + 8 * g); a = __builtin_amdgcn_mfma_f32_16x16x32_bf16(kf, bv[ks], a, 0, 0, 0); }
;             Sacc[dt] = a; }
.Lp2b_435:
	v_mul_u32_u24_e32 v73, 0x210, v85
	v_lshl_add_u32 v73, v90, 6, v73
	v_and_b32_e32 v74, 15, v83
	v_lshl_add_u32 v73, v74, 2, v73
	v_add_u32_e32 v73, 0xe400, v73
	v_cvt_pk_bf16_f32 v16, v22, v16
	v_cvt_pk_bf16_f32 v17, v17, v18
	s_nop 0
	v_add_u32_e32 v18, v111, v118
	ds_write_b64 v18, v[16:17] offset:46080
	s_waitcnt lgkmcnt(0)
	s_barrier
	ds_read_b128 v[20:23], v135 offset:27648
	ds_read_b128 v[16:19], v135 offset:27712
	ds_read_b128 v[156:159], v136 offset:46080
	ds_read_b128 v[160:163], v136 offset:46144
	ds_read2_b64 v[190:193], v137 offset1:4
	ds_read2_b64 v[194:197], v137 offset0:8 offset1:12
	ds_read_b128 v[164:167], v136 offset:48384
	ds_read_b128 v[168:171], v136 offset:48448
	v_add_u32_e32 v40, 0x800, v137
	ds_read2_b64 v[198:201], v40 offset0:32 offset1:36
	ds_read2_b64 v[202:205], v40 offset0:40 offset1:44
	ds_read_b128 v[172:175], v136 offset:50688
	ds_read_b128 v[176:179], v136 offset:50752
	ds_read_b128 v[180:183], v136 offset:52992
	ds_read_b128 v[184:187], v136 offset:53056
	v_cvt_pk_bf16_f32 v28, v8, v9
	v_cvt_pk_bf16_f32 v29, v10, v11
	v_cvt_pk_bf16_f32 v30, v0, v1
	v_cvt_pk_bf16_f32 v31, v2, v3
	v_cvt_pk_bf16_f32 v24, v4, v5
	v_cvt_pk_bf16_f32 v25, v6, v7
	v_cvt_pk_bf16_f32 v26, v12, v13
	v_cvt_pk_bf16_f32 v27, v14, v15
	s_waitcnt lgkmcnt(11)
	v_mfma_f32_16x16x32_bf16 v[32:35], v[156:159], v[20:23], 0
	s_waitcnt lgkmcnt(10)
	v_mfma_f32_16x16x32_bf16 v[32:35], v[160:163], v[16:19], v[32:35]
	s_waitcnt lgkmcnt(9)
	v_mfma_f32_16x16x32_bf16 v[32:35], v[190:193], v[28:31], v[32:35]
	s_waitcnt lgkmcnt(8)
	v_mfma_f32_16x16x32_bf16 v[32:35], v[194:197], v[24:27], v[32:35]
	v_add_u32_e32 v40, 0x1000, v137
	ds_read2_b64 v[222:225], v40 offset0:64 offset1:68
	ds_read2_b64 v[226:229], v40 offset0:72 offset1:76
	v_add_u32_e32 v40, 0x1800, v137
	ds_read2_b64 v[230:233], v40 offset0:96 offset1:100
	ds_read2_b64 v[234:237], v40 offset0:104 offset1:108
	s_waitcnt lgkmcnt(11)
	v_mfma_f32_16x16x32_bf16 v[36:39], v[164:167], v[20:23], 0
	s_waitcnt lgkmcnt(10)
	v_mfma_f32_16x16x32_bf16 v[36:39], v[168:171], v[16:19], v[36:39]
	s_waitcnt lgkmcnt(9)
	v_mfma_f32_16x16x32_bf16 v[36:39], v[198:201], v[28:31], v[36:39]
	s_waitcnt lgkmcnt(8)
	v_mfma_f32_16x16x32_bf16 v[36:39], v[202:205], v[24:27], v[36:39]
	ds_write_b32 v73, v32
	ds_write_b32 v73, v33 offset:528
	ds_write_b32 v73, v34 offset:1056
	ds_write_b32 v73, v35 offset:1584
	s_waitcnt lgkmcnt(7)
	v_mfma_f32_16x16x32_bf16 v[32:35], v[172:175], v[20:23], 0
	s_waitcnt lgkmcnt(6)
	v_mfma_f32_16x16x32_bf16 v[32:35], v[176:179], v[16:19], v[32:35]
	s_waitcnt lgkmcnt(3)
	v_mfma_f32_16x16x32_bf16 v[32:35], v[222:225], v[28:31], v[32:35]
	s_waitcnt lgkmcnt(2)
	v_mfma_f32_16x16x32_bf16 v[32:35], v[226:229], v[24:27], v[32:35]
	ds_write_b32 v73, v36 offset:8448
	ds_write_b32 v73, v37 offset:8976
	ds_write_b32 v73, v38 offset:9504
	ds_write_b32 v73, v39 offset:10032
	ds_read_b128 v[156:159], v82 offset:55296
	ds_read_b128 v[160:163], v82 offset:55360
	ds_read_b128 v[164:167], v82 offset:55424
	ds_read_b128 v[168:171], v82 offset:55488
	ds_read_b128 v[190:193], v136 offset:18432
	ds_read_b128 v[194:197], v136 offset:18496
	ds_read_b128 v[198:201], v136 offset:20736
	ds_read_b128 v[202:205], v136 offset:20800
	v_mfma_f32_16x16x32_bf16 v[36:39], v[180:183], v[20:23], 0
	v_mfma_f32_16x16x32_bf16 v[36:39], v[184:187], v[16:19], v[36:39]
	s_waitcnt lgkmcnt(9)
	v_mfma_f32_16x16x32_bf16 v[36:39], v[230:233], v[28:31], v[36:39]
	s_waitcnt lgkmcnt(8)
	v_mfma_f32_16x16x32_bf16 v[36:39], v[234:237], v[24:27], v[36:39]
	ds_read_b128 v[172:175], v136 offset:23040
	ds_read_b128 v[176:179], v136 offset:23104
	ds_read_b128 v[180:183], v136 offset:25344
	ds_read_b128 v[184:187], v136 offset:25408
	ds_write_b32 v73, v32 offset:16896
	ds_write_b32 v73, v33 offset:17424
	ds_write_b32 v73, v34 offset:17952
	ds_write_b32 v73, v35 offset:18480
	s_waitcnt lgkmcnt(8)
	v_pk_mul_f32 v[8:9], v[8:9], v[156:157]
	v_pk_mul_f32 v[10:11], v[10:11], v[158:159]
	v_pk_mul_f32 v[0:1], v[0:1], v[160:161]
	v_pk_mul_f32 v[2:3], v[2:3], v[162:163]
	v_pk_mul_f32 v[4:5], v[4:5], v[164:165]
	v_pk_mul_f32 v[6:7], v[6:7], v[166:167]
	v_pk_mul_f32 v[12:13], v[12:13], v[168:169]
	v_pk_mul_f32 v[14:15], v[14:15], v[170:171]
	ds_write_b32 v73, v36 offset:25344
	ds_write_b32 v73, v37 offset:25872
	ds_write_b32 v73, v38 offset:26400
	ds_write_b32 v73, v39 offset:26928
	s_waitcnt lgkmcnt(7)
	v_mfma_f32_16x16x32_bf16 v[8:11], v[190:193], v[20:23], v[8:11]
	s_waitcnt lgkmcnt(6)
	v_mfma_f32_16x16x32_bf16 v[8:11], v[194:197], v[16:19], v[8:11]
	s_waitcnt lgkmcnt(5)
	v_mfma_f32_16x16x32_bf16 v[0:3], v[198:201], v[20:23], v[0:3]
	s_waitcnt lgkmcnt(4)
	v_mfma_f32_16x16x32_bf16 v[0:3], v[202:205], v[16:19], v[0:3]
	s_waitcnt lgkmcnt(3)
	v_mfma_f32_16x16x32_bf16 v[4:7], v[172:175], v[20:23], v[4:7]
	s_waitcnt lgkmcnt(2)
	v_mfma_f32_16x16x32_bf16 v[4:7], v[176:179], v[16:19], v[4:7]
	s_waitcnt lgkmcnt(1)
	v_mfma_f32_16x16x32_bf16 v[12:15], v[180:183], v[20:23], v[12:15]
	s_waitcnt lgkmcnt(0)
	v_mfma_f32_16x16x32_bf16 v[12:15], v[184:187], v[16:19], v[12:15]
	s_add_i32 s51, s51, 1
	s_add_i32 s64, s64, -1
	s_cmp_lg_u32 s51, 4
	s_waitcnt lgkmcnt(0)
	s_barrier
; __device__ void gla_pass2(const Params& p, int l, const bf16_t* proj, bf16_t* ycat, LAS unsigned char* lds) {
;     ...
;         const f32x2 gg = *(const f32x2*)(p.gng + l * 512 + h * 128 + lane * 2);
;         for (int j0 = 0; j0 < 32; j0 += 8) {
;             f32x2 of[8], ob[8]; unsigned rw[8];
; #pragma unroll
;             for (int j = 0; j < 8; ++j) { const int t = seg * SEGLEN + wv * 32 + j0 + j; const size_t oo = (size_t)t * 512 + h * 128 + lane * 2;
;                 of[j] = *(const f32x2*)(OF + oo); ob[j] = *(const f32x2*)(OB + oo); rw[j] = *(const unsigned*)(proj + (size_t)t * NP + GR + h * 128 + lane * 2); }
; #pragma unroll
;             for (int j = 0; j < 8; ++j) { const int t = seg * SEGLEN + wv * 32 + j0 + j;
;                 const float o0 = of[j][0] + ob[j][0], o1 = of[j][1] + ob[j][1];
;                 const float ss = wave_sum(o0 * o0 + o1 * o1);
	v_and_b32_e32 v74, 63, v83
	v_lshlrev_b32_e32 v70, 3, v74
	s_lshl_b32 s40, s66, 3
	v_lshl_add_u32 v72, v90, 14, v70
	v_add_u32_e32 v70, s40, v72
	s_lshl_b32 s40, s66, 2
	v_lshlrev_b32_e32 v71, 2, v74
	v_add_u32_e32 v71, s40, v71
	v_lshl_add_u32 v77, v90, 13, v71
	v_mul_u32_u24_e32 v75, 0x1c000, v90
	v_add_u32_e32 v71, v75, v71
	v_lshlrev_b32_e32 v75, 3, v90
	v_sub_u32_e32 v75, 56, v75
	v_mul_u32_u24_e32 v75, 0x210, v75
	v_lshl_add_u32 v72, v74, 3, v75
	v_add_u32_e32 v72, 0xe400, v72
	v_readlane_b32 s56, v255, 55
	v_readlane_b32 s57, v255, 56
	s_add_u32 s56, s56, s67
	s_addc_u32 s57, s57, 0
	v_lshlrev_b32_e32 v76, 3, v74
	s_nop 2
	global_load_dwordx2 v[58:59], v76, s[56:57]
	s_lshl_b32 s54, s52, 11
	s_add_u32 s54, s54, 0x35861000
	s_add_u32 s54, s86, s54
	s_addc_u32 s55, s87, 0
	global_load_dwordx2 v[16:17], v70, s[54:55]
	global_load_dwordx2 v[18:19], v70, s[54:55] offset:2048
	s_add_u32 s54, s54, 0x1000
	s_addc_u32 s55, s55, 0
	global_load_dwordx2 v[20:21], v70, s[54:55]
	global_load_dwordx2 v[22:23], v70, s[54:55] offset:2048
	s_add_u32 s54, s54, 0x1000
	s_addc_u32 s55, s55, 0
	global_load_dwordx2 v[24:25], v70, s[54:55]
	global_load_dwordx2 v[26:27], v70, s[54:55] offset:2048
	s_add_u32 s54, s54, 0x1000
	s_addc_u32 s55, s55, 0
	global_load_dwordx2 v[28:29], v70, s[54:55]
	global_load_dwordx2 v[30:31], v70, s[54:55] offset:2048
	s_mul_i32 s40, s52, 0x3800
	s_add_u32 s40, s40, 0x20604200
	s_add_u32 s40, s86, s40
	s_addc_u32 s41, s87, 0
	global_load_dword v32, v71, s[40:41]
	s_add_u32 s40, s40, 0x3800
	s_addc_u32 s41, s41, 0
	global_load_dword v33, v71, s[40:41]
	s_add_u32 s40, s40, 0x3800
	s_addc_u32 s41, s41, 0
	global_load_dword v34, v71, s[40:41]
	s_add_u32 s40, s40, 0x3800
	s_addc_u32 s41, s41, 0
	global_load_dword v35, v71, s[40:41]
	s_add_u32 s40, s40, 0x3800
	s_addc_u32 s41, s41, 0
	global_load_dword v36, v71, s[40:41]
	s_add_u32 s40, s40, 0x3800
	s_addc_u32 s41, s41, 0
	global_load_dword v37, v71, s[40:41]
	s_add_u32 s40, s40, 0x3800
	s_addc_u32 s41, s41, 0
	global_load_dword v38, v71, s[40:41]
	s_add_u32 s40, s40, 0x3800
	s_addc_u32 s41, s41, 0
	global_load_dword v39, v71, s[40:41]
	ds_read_b64 v[138:139], v72 offset:3696
	ds_read_b64 v[140:141], v72 offset:3168
	ds_read_b64 v[142:143], v72 offset:2640
	ds_read_b64 v[144:145], v72 offset:2112
	ds_read_b64 v[146:147], v72 offset:1584
	ds_read_b64 v[148:149], v72 offset:1056
	ds_read_b64 v[150:151], v72 offset:528
	ds_read_b64 v[152:153], v72 offset:0
	s_lshl_b32 s54, s52, 10
	s_add_u32 s54, s54, 0x30601000
	s_add_u32 s54, s86, s54
	s_addc_u32 s55, s87, 0
	s_add_u32 s56, s54, 0x1000
	s_addc_u32 s57, s55, 0
	s_waitcnt lgkmcnt(7)
	s_waitcnt vmcnt(8)
	v_add_f32_e32 v16, v16, v138
	v_add_f32_e32 v17, v17, v139
	v_mul_f32_e32 v138, v16, v16
	v_mul_f32_e32 v139, v17, v17
	v_add_f32_e32 v138, v138, v139
	s_waitcnt lgkmcnt(6)
	v_add_f32_e32 v18, v18, v140
	v_add_f32_e32 v19, v19, v141
	v_mul_f32_e32 v140, v18, v18
	v_mul_f32_e32 v141, v19, v19
	v_add_f32_e32 v140, v140, v141
	s_waitcnt lgkmcnt(5)
	v_add_f32_e32 v20, v20, v142
	v_add_f32_e32 v21, v21, v143
	v_mul_f32_e32 v142, v20, v20
	v_mul_f32_e32 v143, v21, v21
	v_add_f32_e32 v142, v142, v143
	s_waitcnt lgkmcnt(4)
	v_add_f32_e32 v22, v22, v144
	v_add_f32_e32 v23, v23, v145
	v_mul_f32_e32 v144, v22, v22
	v_mul_f32_e32 v145, v23, v23
	v_add_f32_e32 v144, v144, v145
	s_waitcnt lgkmcnt(3)
	v_add_f32_e32 v24, v24, v146
	v_add_f32_e32 v25, v25, v147
	v_mul_f32_e32 v146, v24, v24
	v_mul_f32_e32 v147, v25, v25
	v_add_f32_e32 v146, v146, v147
	s_waitcnt lgkmcnt(2)
	v_add_f32_e32 v26, v26, v148
	v_add_f32_e32 v27, v27, v149
	v_mul_f32_e32 v148, v26, v26
	v_mul_f32_e32 v149, v27, v27
	v_add_f32_e32 v148, v148, v149
	s_waitcnt lgkmcnt(1)
	v_add_f32_e32 v28, v28, v150
	v_add_f32_e32 v29, v29, v151
	v_mul_f32_e32 v150, v28, v28
	v_mul_f32_e32 v151, v29, v29
	v_add_f32_e32 v150, v150, v151
	s_waitcnt lgkmcnt(0)
	v_add_f32_e32 v30, v30, v152
	v_add_f32_e32 v31, v31, v153
	v_mul_f32_e32 v152, v30, v30
	v_mul_f32_e32 v153, v31, v31
	v_add_f32_e32 v152, v152, v153
	v_mov_b32_e32 v139, v138
	v_mov_b32_e32 v141, v140
	v_mov_b32_e32 v143, v142
	v_mov_b32_e32 v145, v144
	v_mov_b32_e32 v147, v146
	v_mov_b32_e32 v149, v148
	v_mov_b32_e32 v151, v150
	v_mov_b32_e32 v153, v152
	v_permlane32_swap_b32_e32 v139, v138
	v_permlane32_swap_b32_e32 v141, v140
	v_permlane32_swap_b32_e32 v143, v142
	v_permlane32_swap_b32_e32 v145, v144
	v_permlane32_swap_b32_e32 v147, v146
	v_permlane32_swap_b32_e32 v149, v148
	v_permlane32_swap_b32_e32 v151, v150
	v_permlane32_swap_b32_e32 v153, v152
	v_add_f32_e32 v138, v138, v139
	v_add_f32_e32 v140, v140, v141
	v_add_f32_e32 v142, v142, v143
	v_add_f32_e32 v144, v144, v145
	v_add_f32_e32 v146, v146, v147
	v_add_f32_e32 v148, v148, v149
	v_add_f32_e32 v150, v150, v151
	v_add_f32_e32 v152, v152, v153
	v_mov_b32_e32 v139, v138
	v_mov_b32_e32 v141, v140
	v_mov_b32_e32 v143, v142
	v_mov_b32_e32 v145, v144
	v_mov_b32_e32 v147, v146
	v_mov_b32_e32 v149, v148
	v_mov_b32_e32 v151, v150
	v_mov_b32_e32 v153, v152
	v_permlane16_swap_b32_e32 v139, v138
	v_permlane16_swap_b32_e32 v141, v140
	v_permlane16_swap_b32_e32 v143, v142
	v_permlane16_swap_b32_e32 v145, v144
	v_permlane16_swap_b32_e32 v147, v146
	v_permlane16_swap_b32_e32 v149, v148
	v_permlane16_swap_b32_e32 v151, v150
	v_permlane16_swap_b32_e32 v153, v152
	v_add_f32_e32 v138, v138, v139
	v_add_f32_e32 v140, v140, v141
	v_add_f32_e32 v142, v142, v143
	v_add_f32_e32 v144, v144, v145
	v_add_f32_e32 v146, v146, v147
	v_add_f32_e32 v148, v148, v149
	v_add_f32_e32 v150, v150, v151
	v_add_f32_e32 v152, v152, v153
	v_add_f32_dpp v138, v138, v138 row_ror:8 row_mask:0xf bank_mask:0xf
; __device__ __forceinline__ unsigned cvt_pk_bf16(float lo, float hi) { unsigned r; asm("v_cvt_pk_bf16_f32 %0, %1, %2" : "=v"(r) : "v"(lo), "v"(hi)); return r; }
; __device__ __forceinline__ float bf_lo(unsigned w) { return __uint_as_float(w << 16); }
; __device__ __forceinline__ float bf_hi(unsigned w) { return __uint_as_float(w & 0xffff0000u); }
; __device__ void gla_pass2(const Params& p, int l, const bf16_t* proj, bf16_t* ycat, LAS unsigned char* lds) {
;     ...
;             for (int j = 0; j < 8; ++j) { const int t = seg * SEGLEN + wv * 32 + j0 + j;
;                 const float o0 = of[j][0] + ob[j][0], o1 = of[j][1] + ob[j][1];
;                 const float ss = wave_sum(o0 * o0 + o1 * o1);
;                 const float rs = rsqrtf(ss * (1.0f / 128.0f) + 1e-6f);
;                 const float r0 = bf_lo(rw[j]), r1 = bf_hi(rw[j]);
;                 const float y0 = o0 * rs * gg[0] * (r0 / (1.0f + __expf(-r0))), y1 = o1 * rs * gg[1] * (r1 / (1.0f + __expf(-r1)));
;                 *(unsigned*)(ycat + (size_t)2 * SEQ * 512 + (size_t)t * 512 + h * 128 + lane * 2) = cvt_pk_bf16(y0, y1); } }
	v_add_f32_dpp v140, v140, v140 row_ror:8 row_mask:0xf bank_mask:0xf
	v_add_f32_dpp v142, v142, v142 row_ror:8 row_mask:0xf bank_mask:0xf
	v_add_f32_dpp v144, v144, v144 row_ror:8 row_mask:0xf bank_mask:0xf
	v_add_f32_dpp v146, v146, v146 row_ror:8 row_mask:0xf bank_mask:0xf
	v_add_f32_dpp v148, v148, v148 row_ror:8 row_mask:0xf bank_mask:0xf
	v_add_f32_dpp v150, v150, v150 row_ror:8 row_mask:0xf bank_mask:0xf
	v_add_f32_dpp v152, v152, v152 row_ror:8 row_mask:0xf bank_mask:0xf
	v_add_f32_dpp v138, v138, v138 row_ror:4 row_mask:0xf bank_mask:0xf
	v_add_f32_dpp v140, v140, v140 row_ror:4 row_mask:0xf bank_mask:0xf
	v_add_f32_dpp v142, v142, v142 row_ror:4 row_mask:0xf bank_mask:0xf
	v_add_f32_dpp v144, v144, v144 row_ror:4 row_mask:0xf bank_mask:0xf
	v_add_f32_dpp v146, v146, v146 row_ror:4 row_mask:0xf bank_mask:0xf
	v_add_f32_dpp v148, v148, v148 row_ror:4 row_mask:0xf bank_mask:0xf
	v_add_f32_dpp v150, v150, v150 row_ror:4 row_mask:0xf bank_mask:0xf
	v_add_f32_dpp v152, v152, v152 row_ror:4 row_mask:0xf bank_mask:0xf
	v_add_f32_dpp v138, v138, v138 quad_perm:[2,3,0,1] row_mask:0xf bank_mask:0xf
	v_add_f32_dpp v140, v140, v140 quad_perm:[2,3,0,1] row_mask:0xf bank_mask:0xf
	v_add_f32_dpp v142, v142, v142 quad_perm:[2,3,0,1] row_mask:0xf bank_mask:0xf
	v_add_f32_dpp v144, v144, v144 quad_perm:[2,3,0,1] row_mask:0xf bank_mask:0xf
	v_add_f32_dpp v146, v146, v146 quad_perm:[2,3,0,1] row_mask:0xf bank_mask:0xf
	v_add_f32_dpp v148, v148, v148 quad_perm:[2,3,0,1] row_mask:0xf bank_mask:0xf
	v_add_f32_dpp v150, v150, v150 quad_perm:[2,3,0,1] row_mask:0xf bank_mask:0xf
	v_add_f32_dpp v152, v152, v152 quad_perm:[2,3,0,1] row_mask:0xf bank_mask:0xf
	v_add_f32_dpp v138, v138, v138 quad_perm:[1,0,3,2] row_mask:0xf bank_mask:0xf
	v_add_f32_dpp v140, v140, v140 quad_perm:[1,0,3,2] row_mask:0xf bank_mask:0xf
	v_add_f32_dpp v142, v142, v142 quad_perm:[1,0,3,2] row_mask:0xf bank_mask:0xf
	v_add_f32_dpp v144, v144, v144 quad_perm:[1,0,3,2] row_mask:0xf bank_mask:0xf
	v_add_f32_dpp v146, v146, v146 quad_perm:[1,0,3,2] row_mask:0xf bank_mask:0xf
	v_add_f32_dpp v148, v148, v148 quad_perm:[1,0,3,2] row_mask:0xf bank_mask:0xf
	v_add_f32_dpp v150, v150, v150 quad_perm:[1,0,3,2] row_mask:0xf bank_mask:0xf
	v_add_f32_dpp v152, v152, v152 quad_perm:[1,0,3,2] row_mask:0xf bank_mask:0xf
	s_waitcnt vmcnt(0)
	v_fmamk_f32 v138, v138, 0x3c000000, v212
	v_cmp_gt_f32_e32 vcc, s1, v138
	v_mul_f32_e32 v40, 0x4b800000, v138
	v_lshlrev_b32_e32 v41, 16, v32
	v_cndmask_b32_e32 v138, v138, v40, vcc
	v_rsq_f32_e32 v138, v138
	v_and_b32_e32 v42, 0xffff0000, v32
	v_mul_f32_e32 v40, 0x45800000, v138
	v_mul_f32_e32 v43, 0xbfb8aa3b, v41
	v_cndmask_b32_e32 v138, v138, v40, vcc
	v_exp_f32_e32 v43, v43
	v_mul_f32_e32 v44, 0xbfb8aa3b, v42
	v_exp_f32_e32 v44, v44
	v_mul_f32_e32 v16, v16, v138
	v_mul_f32_e32 v17, v17, v138
	v_add_f32_e32 v43, 1.0, v43
	v_add_f32_e32 v44, 1.0, v44
	v_mul_f32_e32 v16, v58, v16
	v_mul_f32_e32 v17, v59, v17
	v_div_scale_f32 v45, s[40:41], v43, v43, v41
	v_div_scale_f32 v46, s[40:41], v44, v44, v42
	v_rcp_f32_e32 v47, v45
	v_rcp_f32_e32 v48, v46
	v_fma_f32 v49, -v45, v47, 1.0
	v_fma_f32 v50, -v46, v48, 1.0
	v_fmac_f32_e32 v47, v49, v47
	v_fmac_f32_e32 v48, v50, v48
	v_div_scale_f32 v49, vcc, v41, v43, v41
	v_mul_f32_e32 v51, v49, v47
	v_fma_f32 v53, -v45, v51, v49
	v_fmac_f32_e32 v51, v53, v47
	v_fma_f32 v45, -v45, v51, v49
	v_div_fmas_f32 v45, v45, v47, v51
	v_div_fixup_f32 v41, v45, v43, v41
	v_div_scale_f32 v50, vcc, v42, v44, v42
	v_mul_f32_e32 v52, v50, v48
	v_fma_f32 v53, -v46, v52, v50
	v_fmac_f32_e32 v52, v53, v48
	v_fma_f32 v46, -v46, v52, v50
	v_div_fmas_f32 v46, v46, v48, v52
	v_div_fixup_f32 v42, v46, v44, v42
	v_mul_f32_e32 v16, v41, v16
	v_mul_f32_e32 v17, v42, v17
	v_cvt_pk_bf16_f32 v60, v16, v17
	global_store_dword v77, v60, s[54:55]
	v_fmamk_f32 v140, v140, 0x3c000000, v212
	v_cmp_gt_f32_e32 vcc, s1, v140
	v_mul_f32_e32 v40, 0x4b800000, v140
	v_lshlrev_b32_e32 v41, 16, v33
	v_cndmask_b32_e32 v140, v140, v40, vcc
	v_rsq_f32_e32 v140, v140
	v_and_b32_e32 v42, 0xffff0000, v33
	v_mul_f32_e32 v40, 0x45800000, v140
	v_mul_f32_e32 v43, 0xbfb8aa3b, v41
	v_cndmask_b32_e32 v140, v140, v40, vcc
	v_exp_f32_e32 v43, v43
	v_mul_f32_e32 v44, 0xbfb8aa3b, v42
	v_exp_f32_e32 v44, v44
	v_mul_f32_e32 v18, v18, v140
	v_mul_f32_e32 v19, v19, v140
	v_add_f32_e32 v43, 1.0, v43
	v_add_f32_e32 v44, 1.0, v44
	v_mul_f32_e32 v18, v58, v18
	v_mul_f32_e32 v19, v59, v19
	v_div_scale_f32 v45, s[40:41], v43, v43, v41
	v_div_scale_f32 v46, s[40:41], v44, v44, v42
	v_rcp_f32_e32 v47, v45
	v_rcp_f32_e32 v48, v46
	v_fma_f32 v49, -v45, v47, 1.0
	v_fma_f32 v50, -v46, v48, 1.0
	v_fmac_f32_e32 v47, v49, v47
	v_fmac_f32_e32 v48, v50, v48
	v_div_scale_f32 v49, vcc, v41, v43, v41
	v_mul_f32_e32 v51, v49, v47
	v_fma_f32 v53, -v45, v51, v49
	v_fmac_f32_e32 v51, v53, v47
	v_fma_f32 v45, -v45, v51, v49
	v_div_fmas_f32 v45, v45, v47, v51
	v_div_fixup_f32 v41, v45, v43, v41
	v_div_scale_f32 v50, vcc, v42, v44, v42
	v_mul_f32_e32 v52, v50, v48
	v_fma_f32 v53, -v46, v52, v50
	v_fmac_f32_e32 v52, v53, v48
	v_fma_f32 v46, -v46, v52, v50
	v_div_fmas_f32 v46, v46, v48, v52
	v_div_fixup_f32 v42, v46, v44, v42
	v_mul_f32_e32 v18, v41, v18
	v_mul_f32_e32 v19, v42, v19
	v_cvt_pk_bf16_f32 v61, v18, v19
	global_store_dword v77, v61, s[54:55] offset:1024
	v_fmamk_f32 v142, v142, 0x3c000000, v212
	v_cmp_gt_f32_e32 vcc, s1, v142
	v_mul_f32_e32 v40, 0x4b800000, v142
	v_lshlrev_b32_e32 v41, 16, v34
	v_cndmask_b32_e32 v142, v142, v40, vcc
	v_rsq_f32_e32 v142, v142
	v_and_b32_e32 v42, 0xffff0000, v34
	v_mul_f32_e32 v40, 0x45800000, v142
	v_mul_f32_e32 v43, 0xbfb8aa3b, v41
	v_cndmask_b32_e32 v142, v142, v40, vcc
; __device__ __forceinline__ unsigned cvt_pk_bf16(float lo, float hi) { unsigned r; asm("v_cvt_pk_bf16_f32 %0, %1, %2" : "=v"(r) : "v"(lo), "v"(hi)); return r; }
; __device__ __forceinline__ float bf_lo(unsigned w) { return __uint_as_float(w << 16); }
; __device__ __forceinline__ float bf_hi(unsigned w) { return __uint_as_float(w & 0xffff0000u); }
; __device__ void gla_pass2(const Params& p, int l, const bf16_t* proj, bf16_t* ycat, LAS unsigned char* lds) {
;     ...
;             for (int j = 0; j < 8; ++j) { const int t = seg * SEGLEN + wv * 32 + j0 + j;
;                 const float o0 = of[j][0] + ob[j][0], o1 = of[j][1] + ob[j][1];
;                 const float ss = wave_sum(o0 * o0 + o1 * o1);
;                 const float rs = rsqrtf(ss * (1.0f / 128.0f) + 1e-6f);
;                 const float r0 = bf_lo(rw[j]), r1 = bf_hi(rw[j]);
;                 const float y0 = o0 * rs * gg[0] * (r0 / (1.0f + __expf(-r0))), y1 = o1 * rs * gg[1] * (r1 / (1.0f + __expf(-r1)));
;                 *(unsigned*)(ycat + (size_t)2 * SEQ * 512 + (size_t)t * 512 + h * 128 + lane * 2) = cvt_pk_bf16(y0, y1); } }
	v_exp_f32_e32 v43, v43
	v_mul_f32_e32 v44, 0xbfb8aa3b, v42
	v_exp_f32_e32 v44, v44
	v_mul_f32_e32 v20, v20, v142
	v_mul_f32_e32 v21, v21, v142
	v_add_f32_e32 v43, 1.0, v43
	v_add_f32_e32 v44, 1.0, v44
	v_mul_f32_e32 v20, v58, v20
	v_mul_f32_e32 v21, v59, v21
	v_div_scale_f32 v45, s[40:41], v43, v43, v41
	v_div_scale_f32 v46, s[40:41], v44, v44, v42
	v_rcp_f32_e32 v47, v45
	v_rcp_f32_e32 v48, v46
	v_fma_f32 v49, -v45, v47, 1.0
	v_fma_f32 v50, -v46, v48, 1.0
	v_fmac_f32_e32 v47, v49, v47
	v_fmac_f32_e32 v48, v50, v48
	v_div_scale_f32 v49, vcc, v41, v43, v41
	v_mul_f32_e32 v51, v49, v47
	v_fma_f32 v53, -v45, v51, v49
	v_fmac_f32_e32 v51, v53, v47
	v_fma_f32 v45, -v45, v51, v49
	v_div_fmas_f32 v45, v45, v47, v51
	v_div_fixup_f32 v41, v45, v43, v41
	v_div_scale_f32 v50, vcc, v42, v44, v42
	v_mul_f32_e32 v52, v50, v48
	v_fma_f32 v53, -v46, v52, v50
	v_fmac_f32_e32 v52, v53, v48
	v_fma_f32 v46, -v46, v52, v50
	v_div_fmas_f32 v46, v46, v48, v52
	v_div_fixup_f32 v42, v46, v44, v42
	v_mul_f32_e32 v20, v41, v20
	v_mul_f32_e32 v21, v42, v21
	v_cvt_pk_bf16_f32 v62, v20, v21
	global_store_dword v77, v62, s[54:55] offset:2048
	v_fmamk_f32 v144, v144, 0x3c000000, v212
	v_cmp_gt_f32_e32 vcc, s1, v144
	v_mul_f32_e32 v40, 0x4b800000, v144
	v_lshlrev_b32_e32 v41, 16, v35
	v_cndmask_b32_e32 v144, v144, v40, vcc
	v_rsq_f32_e32 v144, v144
	v_and_b32_e32 v42, 0xffff0000, v35
	v_mul_f32_e32 v40, 0x45800000, v144
	v_mul_f32_e32 v43, 0xbfb8aa3b, v41
	v_cndmask_b32_e32 v144, v144, v40, vcc
	v_exp_f32_e32 v43, v43
	v_mul_f32_e32 v44, 0xbfb8aa3b, v42
	v_exp_f32_e32 v44, v44
	v_mul_f32_e32 v22, v22, v144
	v_mul_f32_e32 v23, v23, v144
	v_add_f32_e32 v43, 1.0, v43
	v_add_f32_e32 v44, 1.0, v44
	v_mul_f32_e32 v22, v58, v22
	v_mul_f32_e32 v23, v59, v23
	v_div_scale_f32 v45, s[40:41], v43, v43, v41
	v_div_scale_f32 v46, s[40:41], v44, v44, v42
	v_rcp_f32_e32 v47, v45
	v_rcp_f32_e32 v48, v46
	v_fma_f32 v49, -v45, v47, 1.0
	v_fma_f32 v50, -v46, v48, 1.0
	v_fmac_f32_e32 v47, v49, v47
	v_fmac_f32_e32 v48, v50, v48
	v_div_scale_f32 v49, vcc, v41, v43, v41
	v_mul_f32_e32 v51, v49, v47
	v_fma_f32 v53, -v45, v51, v49
	v_fmac_f32_e32 v51, v53, v47
	v_fma_f32 v45, -v45, v51, v49
	v_div_fmas_f32 v45, v45, v47, v51
	v_div_fixup_f32 v41, v45, v43, v41
	v_div_scale_f32 v50, vcc, v42, v44, v42
	v_mul_f32_e32 v52, v50, v48
	v_fma_f32 v53, -v46, v52, v50
	v_fmac_f32_e32 v52, v53, v48
	v_fma_f32 v46, -v46, v52, v50
	v_div_fmas_f32 v46, v46, v48, v52
	v_div_fixup_f32 v42, v46, v44, v42
	v_mul_f32_e32 v22, v41, v22
	v_mul_f32_e32 v23, v42, v23
	v_cvt_pk_bf16_f32 v63, v22, v23
	global_store_dword v77, v63, s[54:55] offset:3072
	v_fmamk_f32 v146, v146, 0x3c000000, v212
	v_cmp_gt_f32_e32 vcc, s1, v146
	v_mul_f32_e32 v40, 0x4b800000, v146
	v_lshlrev_b32_e32 v41, 16, v36
	v_cndmask_b32_e32 v146, v146, v40, vcc
	v_rsq_f32_e32 v146, v146
	v_and_b32_e32 v42, 0xffff0000, v36
	v_mul_f32_e32 v40, 0x45800000, v146
	v_mul_f32_e32 v43, 0xbfb8aa3b, v41
	v_cndmask_b32_e32 v146, v146, v40, vcc
	v_exp_f32_e32 v43, v43
	v_mul_f32_e32 v44, 0xbfb8aa3b, v42
	v_exp_f32_e32 v44, v44
	v_mul_f32_e32 v24, v24, v146
	v_mul_f32_e32 v25, v25, v146
	v_add_f32_e32 v43, 1.0, v43
	v_add_f32_e32 v44, 1.0, v44
	v_mul_f32_e32 v24, v58, v24
	v_mul_f32_e32 v25, v59, v25
	v_div_scale_f32 v45, s[40:41], v43, v43, v41
	v_div_scale_f32 v46, s[40:41], v44, v44, v42
	v_rcp_f32_e32 v47, v45
	v_rcp_f32_e32 v48, v46
	v_fma_f32 v49, -v45, v47, 1.0
	v_fma_f32 v50, -v46, v48, 1.0
	v_fmac_f32_e32 v47, v49, v47
	v_fmac_f32_e32 v48, v50, v48
	v_div_scale_f32 v49, vcc, v41, v43, v41
	v_mul_f32_e32 v51, v49, v47
	v_fma_f32 v53, -v45, v51, v49
	v_fmac_f32_e32 v51, v53, v47
	v_fma_f32 v45, -v45, v51, v49
	v_div_fmas_f32 v45, v45, v47, v51
	v_div_fixup_f32 v41, v45, v43, v41
	v_div_scale_f32 v50, vcc, v42, v44, v42
	v_mul_f32_e32 v52, v50, v48
	v_fma_f32 v53, -v46, v52, v50
	v_fmac_f32_e32 v52, v53, v48
	v_fma_f32 v46, -v46, v52, v50
	v_div_fmas_f32 v46, v46, v48, v52
	v_div_fixup_f32 v42, v46, v44, v42
	v_mul_f32_e32 v24, v41, v24
	v_mul_f32_e32 v25, v42, v25
	v_cvt_pk_bf16_f32 v64, v24, v25
	global_store_dword v77, v64, s[56:57]
	v_fmamk_f32 v148, v148, 0x3c000000, v212
	v_cmp_gt_f32_e32 vcc, s1, v148
	v_mul_f32_e32 v40, 0x4b800000, v148
	v_lshlrev_b32_e32 v41, 16, v37
	v_cndmask_b32_e32 v148, v148, v40, vcc
	v_rsq_f32_e32 v148, v148
	v_and_b32_e32 v42, 0xffff0000, v37
	v_mul_f32_e32 v40, 0x45800000, v148
	v_mul_f32_e32 v43, 0xbfb8aa3b, v41
	v_cndmask_b32_e32 v148, v148, v40, vcc
	v_exp_f32_e32 v43, v43
	v_mul_f32_e32 v44, 0xbfb8aa3b, v42
	v_exp_f32_e32 v44, v44
	v_mul_f32_e32 v26, v26, v148
	v_mul_f32_e32 v27, v27, v148
	v_add_f32_e32 v43, 1.0, v43
	v_add_f32_e32 v44, 1.0, v44
	v_mul_f32_e32 v26, v58, v26
	v_mul_f32_e32 v27, v59, v27
	v_div_scale_f32 v45, s[40:41], v43, v43, v41
	v_div_scale_f32 v46, s[40:41], v44, v44, v42
	v_rcp_f32_e32 v47, v45
	v_rcp_f32_e32 v48, v46
	v_fma_f32 v49, -v45, v47, 1.0
	v_fma_f32 v50, -v46, v48, 1.0
	v_fmac_f32_e32 v47, v49, v47
	v_fmac_f32_e32 v48, v50, v48
	v_div_scale_f32 v49, vcc, v41, v43, v41
	v_mul_f32_e32 v51, v49, v47
	v_fma_f32 v53, -v45, v51, v49
	v_fmac_f32_e32 v51, v53, v47
	v_fma_f32 v45, -v45, v51, v49
	v_div_fmas_f32 v45, v45, v47, v51
	v_div_fixup_f32 v41, v45, v43, v41
	v_div_scale_f32 v50, vcc, v42, v44, v42
	v_mul_f32_e32 v52, v50, v48
	v_fma_f32 v53, -v46, v52, v50
	v_fmac_f32_e32 v52, v53, v48
	v_fma_f32 v46, -v46, v52, v50
	v_div_fmas_f32 v46, v46, v48, v52
	v_div_fixup_f32 v42, v46, v44, v42
	v_mul_f32_e32 v26, v41, v26
	v_mul_f32_e32 v27, v42, v27
	v_cvt_pk_bf16_f32 v65, v26, v27
	global_store_dword v77, v65, s[56:57] offset:1024
	v_fmamk_f32 v150, v150, 0x3c000000, v212
; template <bool OUT>
; __device__ __forceinline__ void gla_chunks(const Params& p, int l, const bf16_t* proj, LAS unsigned char* lds, int seg, int h, int dir, f32x4 (&Sacc)[4], float* outbuf, float& alog) {
;     ...
;         for (int ks = 0; ks < 2; ++ks) bv[ks] = *(const LAS bf16x8*)(VT + (16 * wv + fr) * GP + 32 * ks + 8 * g);
;         if (OUT) {
;             bf16x8 bs[2];
; #pragma unroll
;             for (int m = 0; m < 2; ++m) { u32x4 sw; sw.x = cvt_pk_bf16_mfma(Sacc[2 * m][0], Sacc[2 * m][1]); sw.y = cvt_pk_bf16_mfma(Sacc[2 * m][2], Sacc[2 * m][3]); sw.z = cvt_pk_bf16_mfma(Sacc[2 * m + 1][0], Sacc[2 * m + 1][1]); sw.w = cvt_pk_bf16_mfma(Sacc[2 * m + 1][2], Sacc[2 * m + 1][3]); bs[m] = __builtin_bit_cast(bf16x8, sw); }
; #pragma unroll
;             for (int it = 0; it < 4; ++it) { f32x4 o = {0.f, 0.f, 0.f, 0.f};
; #pragma unroll
;                 for (int ks = 0; ks < 2; ++ks) { const bf16x8 pf = *(const LAS bf16x8*)(PP + (it * 16 + fr) * GP + 32 * ks + 8 * g); o = __builtin_amdgcn_mfma_f32_16x16x32_bf16(pf, bv[ks], o, 0, 0, 0); }
; #pragma unroll
;                 for (int m = 0; m < 2; ++m) { const LAS bf16_t* qp = QT + (it * 16 + fr) * GP + 32 * m + 4 * g; const u32x2 lo = *(const LAS u32x2*)qp, hi = *(const LAS u32x2*)(qp + 16);
;                     u32x4 qw; qw.x = lo.x; qw.y = lo.y; qw.z = hi.x; qw.w = hi.y; o = __builtin_amdgcn_mfma_f32_16x16x32_bf16(__builtin_bit_cast(bf16x8, qw), bs[m], o, 0, 0, 0); }
; #pragma unroll
;                 for (int r = 0; r < 4; ++r) { const int i = it * 16 + 4 * g + r, t = dir ? t0 + 63 - i : t0 + i; outbuf[(size_t)t * 512 + h * 128 + 16 * wv + fr] = o[r]; } }
; __device__ void gla_pass2(const Params& p, int l, const bf16_t* proj, bf16_t* ycat, LAS unsigned char* lds) {
;     ...
;             for (int j = 0; j < 8; ++j) { const int t = seg * SEGLEN + wv * 32 + j0 + j;
;                 const float o0 = of[j][0] + ob[j][0], o1 = of[j][1] + ob[j][1];
;                 const float ss = wave_sum(o0 * o0 + o1 * o1);
;                 const float rs = rsqrtf(ss * (1.0f / 128.0f) + 1e-6f);
;                 const float r0 = bf_lo(rw[j]), r1 = bf_hi(rw[j]);
;                 const float y0 = o0 * rs * gg[0] * (r0 / (1.0f + __expf(-r0))), y1 = o1 * rs * gg[1] * (r1 / (1.0f + __expf(-r1)));
;                 *(unsigned*)(ycat + (size_t)2 * SEQ * 512 + (size_t)t * 512 + h * 128 + lane * 2) = cvt_pk_bf16(y0, y1); } }
	v_cmp_gt_f32_e32 vcc, s1, v150
	v_mul_f32_e32 v40, 0x4b800000, v150
	v_lshlrev_b32_e32 v41, 16, v38
	v_cndmask_b32_e32 v150, v150, v40, vcc
	v_rsq_f32_e32 v150, v150
	v_and_b32_e32 v42, 0xffff0000, v38
	v_mul_f32_e32 v40, 0x45800000, v150
	v_mul_f32_e32 v43, 0xbfb8aa3b, v41
	v_cndmask_b32_e32 v150, v150, v40, vcc
	v_exp_f32_e32 v43, v43
	v_mul_f32_e32 v44, 0xbfb8aa3b, v42
	v_exp_f32_e32 v44, v44
	v_mul_f32_e32 v28, v28, v150
	v_mul_f32_e32 v29, v29, v150
	v_add_f32_e32 v43, 1.0, v43
	v_add_f32_e32 v44, 1.0, v44
	v_mul_f32_e32 v28, v58, v28
	v_mul_f32_e32 v29, v59, v29
	v_div_scale_f32 v45, s[40:41], v43, v43, v41
	v_div_scale_f32 v46, s[40:41], v44, v44, v42
	v_rcp_f32_e32 v47, v45
	v_rcp_f32_e32 v48, v46
	v_fma_f32 v49, -v45, v47, 1.0
	v_fma_f32 v50, -v46, v48, 1.0
	v_fmac_f32_e32 v47, v49, v47
	v_fmac_f32_e32 v48, v50, v48
	v_div_scale_f32 v49, vcc, v41, v43, v41
	v_mul_f32_e32 v51, v49, v47
	v_fma_f32 v53, -v45, v51, v49
	v_fmac_f32_e32 v51, v53, v47
	v_fma_f32 v45, -v45, v51, v49
	v_div_fmas_f32 v45, v45, v47, v51
	v_div_fixup_f32 v41, v45, v43, v41
	v_div_scale_f32 v50, vcc, v42, v44, v42
	v_mul_f32_e32 v52, v50, v48
	v_fma_f32 v53, -v46, v52, v50
	v_fmac_f32_e32 v52, v53, v48
	v_fma_f32 v46, -v46, v52, v50
	v_div_fmas_f32 v46, v46, v48, v52
	v_div_fixup_f32 v42, v46, v44, v42
	v_mul_f32_e32 v28, v41, v28
	v_mul_f32_e32 v29, v42, v29
	v_cvt_pk_bf16_f32 v66, v28, v29
	global_store_dword v77, v66, s[56:57] offset:2048
	v_fmamk_f32 v152, v152, 0x3c000000, v212
	v_cmp_gt_f32_e32 vcc, s1, v152
	v_mul_f32_e32 v40, 0x4b800000, v152
	v_lshlrev_b32_e32 v41, 16, v39
	v_cndmask_b32_e32 v152, v152, v40, vcc
	v_rsq_f32_e32 v152, v152
	v_and_b32_e32 v42, 0xffff0000, v39
	v_mul_f32_e32 v40, 0x45800000, v152
	v_mul_f32_e32 v43, 0xbfb8aa3b, v41
	v_cndmask_b32_e32 v152, v152, v40, vcc
	v_exp_f32_e32 v43, v43
	v_mul_f32_e32 v44, 0xbfb8aa3b, v42
	v_exp_f32_e32 v44, v44
	v_mul_f32_e32 v30, v30, v152
	v_mul_f32_e32 v31, v31, v152
	v_add_f32_e32 v43, 1.0, v43
	v_add_f32_e32 v44, 1.0, v44
	v_mul_f32_e32 v30, v58, v30
	v_mul_f32_e32 v31, v59, v31
	v_div_scale_f32 v45, s[40:41], v43, v43, v41
	v_div_scale_f32 v46, s[40:41], v44, v44, v42
	v_rcp_f32_e32 v47, v45
	v_rcp_f32_e32 v48, v46
	v_fma_f32 v49, -v45, v47, 1.0
	v_fma_f32 v50, -v46, v48, 1.0
	v_fmac_f32_e32 v47, v49, v47
	v_fmac_f32_e32 v48, v50, v48
	v_div_scale_f32 v49, vcc, v41, v43, v41
	v_mul_f32_e32 v51, v49, v47
	v_fma_f32 v53, -v45, v51, v49
	v_fmac_f32_e32 v51, v53, v47
	v_fma_f32 v45, -v45, v51, v49
	v_div_fmas_f32 v45, v45, v47, v51
	v_div_fixup_f32 v41, v45, v43, v41
	v_div_scale_f32 v50, vcc, v42, v44, v42
	v_mul_f32_e32 v52, v50, v48
	v_fma_f32 v53, -v46, v52, v50
	v_fmac_f32_e32 v52, v53, v48
	v_fma_f32 v46, -v46, v52, v50
	v_div_fmas_f32 v46, v46, v48, v52
	v_div_fixup_f32 v42, v46, v44, v42
	v_mul_f32_e32 v30, v41, v30
	v_mul_f32_e32 v31, v42, v31
	v_cvt_pk_bf16_f32 v67, v30, v31
	global_store_dword v77, v67, s[56:57] offset:3072
	s_cmp_lg_u32 s51, 4
	s_cbranch_scc0 .LBB0_433
	s_branch .LBB0_436
.LBB0_435:
	s_and_b64 s[40:41], s[42:43], exec
	s_cbranch_scc0 .Lp2b_435
	v_cvt_pk_bf16_f32 v16, v22, v16
	v_cvt_pk_bf16_f32 v17, v17, v18
	s_nop 0
	v_add_u32_e32 v18, v111, v118
	ds_write_b64 v18, v[16:17] offset:46080
	s_waitcnt lgkmcnt(0)
	s_barrier
	ds_read_b128 v[20:23], v135 offset:27648
	ds_read_b128 v[16:19], v135 offset:27712
	ds_read_b128 v[156:159], v136 offset:46080
	ds_read_b128 v[160:163], v136 offset:46144
	ds_read2_b64 v[190:193], v137 offset1:4
	ds_read2_b64 v[194:197], v137 offset0:8 offset1:12
	ds_read_b128 v[164:167], v136 offset:48384
	ds_read_b128 v[168:171], v136 offset:48448
	v_add_u32_e32 v40, 0x800, v137
	ds_read2_b64 v[198:201], v40 offset0:32 offset1:36
	ds_read2_b64 v[202:205], v40 offset0:40 offset1:44
	ds_read_b128 v[172:175], v136 offset:50688
	ds_read_b128 v[176:179], v136 offset:50752
	ds_read_b128 v[180:183], v136 offset:52992
	ds_read_b128 v[184:187], v136 offset:53056
	v_cvt_pk_bf16_f32 v28, v8, v9
	v_cvt_pk_bf16_f32 v29, v10, v11
	v_cvt_pk_bf16_f32 v30, v0, v1
	v_cvt_pk_bf16_f32 v31, v2, v3
	v_cvt_pk_bf16_f32 v24, v4, v5
	v_cvt_pk_bf16_f32 v25, v6, v7
	v_cvt_pk_bf16_f32 v26, v12, v13
	v_cvt_pk_bf16_f32 v27, v14, v15
	s_waitcnt lgkmcnt(11)
	v_mfma_f32_16x16x32_bf16 v[32:35], v[156:159], v[20:23], 0
	s_waitcnt lgkmcnt(10)
	v_mfma_f32_16x16x32_bf16 v[32:35], v[160:163], v[16:19], v[32:35]
	s_waitcnt lgkmcnt(9)
	v_mfma_f32_16x16x32_bf16 v[32:35], v[190:193], v[28:31], v[32:35]
	s_waitcnt lgkmcnt(8)
	v_mfma_f32_16x16x32_bf16 v[32:35], v[194:197], v[24:27], v[32:35]
	v_add_u32_e32 v40, 0x1000, v137
	ds_read2_b64 v[222:225], v40 offset0:64 offset1:68
	ds_read2_b64 v[226:229], v40 offset0:72 offset1:76
	v_add_u32_e32 v40, 0x1800, v137
	ds_read2_b64 v[230:233], v40 offset0:96 offset1:100
	ds_read2_b64 v[234:237], v40 offset0:104 offset1:108
	s_waitcnt lgkmcnt(11)
	v_mfma_f32_16x16x32_bf16 v[36:39], v[164:167], v[20:23], 0
	s_waitcnt lgkmcnt(10)
	v_mfma_f32_16x16x32_bf16 v[36:39], v[168:171], v[16:19], v[36:39]
	s_waitcnt lgkmcnt(9)
	v_mfma_f32_16x16x32_bf16 v[36:39], v[198:201], v[28:31], v[36:39]
	s_waitcnt lgkmcnt(8)
; #define LAS __attribute__((address_space(3)))
; template <bool OUT>
; __device__ __forceinline__ void gla_chunks(const Params& p, int l, const bf16_t* proj, LAS unsigned char* lds, int seg, int h, int dir, f32x4 (&Sacc)[4], float* outbuf, float& alog) {
;     ...
;             for (int it = 0; it < 4; ++it) { f32x4 o = {0.f, 0.f, 0.f, 0.f};
; #pragma unroll
;                 for (int ks = 0; ks < 2; ++ks) { const bf16x8 pf = *(const LAS bf16x8*)(PP + (it * 16 + fr) * GP + 32 * ks + 8 * g); o = __builtin_amdgcn_mfma_f32_16x16x32_bf16(pf, bv[ks], o, 0, 0, 0); }
; #pragma unroll
;                 for (int m = 0; m < 2; ++m) { const LAS bf16_t* qp = QT + (it * 16 + fr) * GP + 32 * m + 4 * g; const u32x2 lo = *(const LAS u32x2*)qp, hi = *(const LAS u32x2*)(qp + 16);
;                     u32x4 qw; qw.x = lo.x; qw.y = lo.y; qw.z = hi.x; qw.w = hi.y; o = __builtin_amdgcn_mfma_f32_16x16x32_bf16(__builtin_bit_cast(bf16x8, qw), bs[m], o, 0, 0, 0); }
; #pragma unroll
;                 for (int r = 0; r < 4; ++r) { const int i = it * 16 + 4 * g + r, t = dir ? t0 + 63 - i : t0 + i; outbuf[(size_t)t * 512 + h * 128 + 16 * wv + fr] = o[r]; } }
;         }
; #pragma unroll
;         for (int dt = 0; dt < 4; ++dt) { const f32x4 eb = *(const LAS f32x4*)(EBL + dt * 16 + 4 * g); f32x4 a = Sacc[dt] * eb;
; #pragma unroll
;             for (int ks = 0; ks < 2; ++ks) { const bf16x8 kf = *(const LAS bf16x8*)(KH + (dt * 16 + fr) * GP + 32 * ks + 8 * g); a = __builtin_amdgcn_mfma_f32_16x16x32_bf16(kf, bv[ks], a, 0, 0, 0); }
;             Sacc[dt] = a; }
	v_mfma_f32_16x16x32_bf16 v[36:39], v[202:205], v[24:27], v[36:39]
	v_sub_u32_e32 v238, s53, v85
	v_or_b32_e32 v239, s52, v85
	v_cndmask_b32_e64 v238, v238, v239, s[42:43]
	v_ashrrev_i32_e32 v239, 31, v238
	v_lshlrev_b64 v[238:239], 11, v[238:239]
	v_lshl_add_u64 v[238:239], v[86:87], 0, v[238:239]
	global_store_dword v[238:239], v32, off
	v_sub_u32_e32 v240, s53, v119
	v_or_b32_e32 v241, s52, v119
	v_cndmask_b32_e64 v240, v240, v241, s[42:43]
	v_ashrrev_i32_e32 v241, 31, v240
	v_lshlrev_b64 v[240:241], 11, v[240:241]
	v_lshl_add_u64 v[240:241], v[86:87], 0, v[240:241]
	global_store_dword v[240:241], v33, off
	v_sub_u32_e32 v238, s53, v120
	v_or_b32_e32 v239, s52, v120
	v_cndmask_b32_e64 v238, v238, v239, s[42:43]
	v_ashrrev_i32_e32 v239, 31, v238
	v_lshlrev_b64 v[238:239], 11, v[238:239]
	v_lshl_add_u64 v[238:239], v[86:87], 0, v[238:239]
	global_store_dword v[238:239], v34, off
	v_sub_u32_e32 v240, s53, v121
	v_or_b32_e32 v241, s52, v121
	v_cndmask_b32_e64 v240, v240, v241, s[42:43]
	v_ashrrev_i32_e32 v241, 31, v240
	v_lshlrev_b64 v[240:241], 11, v[240:241]
	v_lshl_add_u64 v[240:241], v[86:87], 0, v[240:241]
	global_store_dword v[240:241], v35, off
	s_waitcnt lgkmcnt(7)
	v_mfma_f32_16x16x32_bf16 v[32:35], v[172:175], v[20:23], 0
	s_waitcnt lgkmcnt(6)
	v_mfma_f32_16x16x32_bf16 v[32:35], v[176:179], v[16:19], v[32:35]
	s_waitcnt lgkmcnt(3)
	v_mfma_f32_16x16x32_bf16 v[32:35], v[222:225], v[28:31], v[32:35]
	s_waitcnt lgkmcnt(2)
	v_mfma_f32_16x16x32_bf16 v[32:35], v[226:229], v[24:27], v[32:35]
	v_sub_u32_e32 v238, s53, v122
	v_or_b32_e32 v239, s52, v122
	v_cndmask_b32_e64 v238, v238, v239, s[42:43]
	v_ashrrev_i32_e32 v239, 31, v238
	v_lshlrev_b64 v[238:239], 11, v[238:239]
	v_lshl_add_u64 v[238:239], v[86:87], 0, v[238:239]
	global_store_dword v[238:239], v36, off
	v_sub_u32_e32 v240, s53, v123
	v_or_b32_e32 v241, s52, v123
	v_cndmask_b32_e64 v240, v240, v241, s[42:43]
	v_ashrrev_i32_e32 v241, 31, v240
	v_lshlrev_b64 v[240:241], 11, v[240:241]
	v_lshl_add_u64 v[240:241], v[86:87], 0, v[240:241]
	global_store_dword v[240:241], v37, off
	v_sub_u32_e32 v238, s53, v124
	v_or_b32_e32 v239, s52, v124
	v_cndmask_b32_e64 v238, v238, v239, s[42:43]
	v_ashrrev_i32_e32 v239, 31, v238
	v_lshlrev_b64 v[238:239], 11, v[238:239]
	v_lshl_add_u64 v[238:239], v[86:87], 0, v[238:239]
	global_store_dword v[238:239], v38, off
	v_sub_u32_e32 v240, s53, v125
	v_or_b32_e32 v241, s52, v125
	v_cndmask_b32_e64 v240, v240, v241, s[42:43]
	v_ashrrev_i32_e32 v241, 31, v240
	v_lshlrev_b64 v[240:241], 11, v[240:241]
	v_lshl_add_u64 v[240:241], v[86:87], 0, v[240:241]
	global_store_dword v[240:241], v39, off
	ds_read_b128 v[156:159], v82 offset:55296
	ds_read_b128 v[160:163], v82 offset:55360
	ds_read_b128 v[164:167], v82 offset:55424
	ds_read_b128 v[168:171], v82 offset:55488
	ds_read_b128 v[190:193], v136 offset:18432
	ds_read_b128 v[194:197], v136 offset:18496
	ds_read_b128 v[198:201], v136 offset:20736
	ds_read_b128 v[202:205], v136 offset:20800
	v_mfma_f32_16x16x32_bf16 v[36:39], v[180:183], v[20:23], 0
	v_mfma_f32_16x16x32_bf16 v[36:39], v[184:187], v[16:19], v[36:39]
	s_waitcnt lgkmcnt(9)
	v_mfma_f32_16x16x32_bf16 v[36:39], v[230:233], v[28:31], v[36:39]
	s_waitcnt lgkmcnt(8)
	v_mfma_f32_16x16x32_bf16 v[36:39], v[234:237], v[24:27], v[36:39]
	ds_read_b128 v[172:175], v136 offset:23040
	ds_read_b128 v[176:179], v136 offset:23104
	ds_read_b128 v[180:183], v136 offset:25344
	ds_read_b128 v[184:187], v136 offset:25408
	v_sub_u32_e32 v238, s53, v126
	v_or_b32_e32 v239, s52, v126
	v_cndmask_b32_e64 v238, v238, v239, s[42:43]
	v_ashrrev_i32_e32 v239, 31, v238
	v_lshlrev_b64 v[238:239], 11, v[238:239]
	v_lshl_add_u64 v[238:239], v[86:87], 0, v[238:239]
	global_store_dword v[238:239], v32, off
	v_sub_u32_e32 v240, s53, v127
	v_or_b32_e32 v241, s52, v127
	v_cndmask_b32_e64 v240, v240, v241, s[42:43]
	v_ashrrev_i32_e32 v241, 31, v240
	v_lshlrev_b64 v[240:241], 11, v[240:241]
	v_lshl_add_u64 v[240:241], v[86:87], 0, v[240:241]
	global_store_dword v[240:241], v33, off
	v_sub_u32_e32 v238, s53, v128
	v_or_b32_e32 v239, s52, v128
	v_cndmask_b32_e64 v238, v238, v239, s[42:43]
	v_ashrrev_i32_e32 v239, 31, v238
	v_lshlrev_b64 v[238:239], 11, v[238:239]
	v_lshl_add_u64 v[238:239], v[86:87], 0, v[238:239]
	global_store_dword v[238:239], v34, off
	v_sub_u32_e32 v240, s53, v129
	v_or_b32_e32 v241, s52, v129
	v_cndmask_b32_e64 v240, v240, v241, s[42:43]
	v_ashrrev_i32_e32 v241, 31, v240
	v_lshlrev_b64 v[240:241], 11, v[240:241]
	v_lshl_add_u64 v[240:241], v[86:87], 0, v[240:241]
	global_store_dword v[240:241], v35, off
	s_waitcnt lgkmcnt(8)
	v_pk_mul_f32 v[8:9], v[8:9], v[156:157]
	v_pk_mul_f32 v[10:11], v[10:11], v[158:159]
	v_pk_mul_f32 v[0:1], v[0:1], v[160:161]
	v_pk_mul_f32 v[2:3], v[2:3], v[162:163]
	v_pk_mul_f32 v[4:5], v[4:5], v[164:165]
	v_pk_mul_f32 v[6:7], v[6:7], v[166:167]
	v_pk_mul_f32 v[12:13], v[12:13], v[168:169]
	v_pk_mul_f32 v[14:15], v[14:15], v[170:171]
	v_sub_u32_e32 v238, s53, v130
	v_or_b32_e32 v239, s52, v130
	v_cndmask_b32_e64 v238, v238, v239, s[42:43]
	v_ashrrev_i32_e32 v239, 31, v238
	v_lshlrev_b64 v[238:239], 11, v[238:239]
	v_lshl_add_u64 v[238:239], v[86:87], 0, v[238:239]
	global_store_dword v[238:239], v36, off
	v_sub_u32_e32 v240, s53, v131
	v_or_b32_e32 v241, s52, v131
	v_cndmask_b32_e64 v240, v240, v241, s[42:43]
	v_ashrrev_i32_e32 v241, 31, v240
	v_lshlrev_b64 v[240:241], 11, v[240:241]
	v_lshl_add_u64 v[240:241], v[86:87], 0, v[240:241]
	global_store_dword v[240:241], v37, off
	v_sub_u32_e32 v238, s53, v132
	v_or_b32_e32 v239, s52, v132
	v_cndmask_b32_e64 v238, v238, v239, s[42:43]
	v_ashrrev_i32_e32 v239, 31, v238
	v_lshlrev_b64 v[238:239], 11, v[238:239]
	v_lshl_add_u64 v[238:239], v[86:87], 0, v[238:239]
	global_store_dword v[238:239], v38, off
	v_sub_u32_e32 v240, s53, v133
	v_or_b32_e32 v241, s52, v133
	v_cndmask_b32_e64 v240, v240, v241, s[42:43]
	v_ashrrev_i32_e32 v241, 31, v240
	v_lshlrev_b64 v[240:241], 11, v[240:241]
	v_lshl_add_u64 v[240:241], v[86:87], 0, v[240:241]
	global_store_dword v[240:241], v39, off
	s_waitcnt lgkmcnt(7)
	v_mfma_f32_16x16x32_bf16 v[8:11], v[190:193], v[20:23], v[8:11]
	s_waitcnt lgkmcnt(6)
	v_mfma_f32_16x16x32_bf16 v[8:11], v[194:197], v[16:19], v[8:11]
	s_waitcnt lgkmcnt(5)
	v_mfma_f32_16x16x32_bf16 v[0:3], v[198:201], v[20:23], v[0:3]
	s_waitcnt lgkmcnt(4)
	v_mfma_f32_16x16x32_bf16 v[0:3], v[202:205], v[16:19], v[0:3]
	s_waitcnt lgkmcnt(3)
	v_mfma_f32_16x16x32_bf16 v[4:7], v[172:175], v[20:23], v[4:7]
	s_waitcnt lgkmcnt(2)
	v_mfma_f32_16x16x32_bf16 v[4:7], v[176:179], v[16:19], v[4:7]
	s_waitcnt lgkmcnt(1)
	v_mfma_f32_16x16x32_bf16 v[12:15], v[180:183], v[20:23], v[12:15]
	s_waitcnt lgkmcnt(0)
	v_mfma_f32_16x16x32_bf16 v[12:15], v[184:187], v[16:19], v[12:15]
	s_add_i32 s51, s51, 1
	s_add_i32 s64, s64, -1
	s_cmp_lg_u32 s51, 4
	s_waitcnt lgkmcnt(0)
	s_barrier
	s_cbranch_scc0 .LBB0_433

; __device__ __forceinline__ unsigned cvt_pk_bf16(float lo, float hi) { unsigned r; asm("v_cvt_pk_bf16_f32 %0, %1, %2" : "=v"(r) : "v"(lo), "v"(hi)); return r; }
; __device__ __forceinline__ float bf_lo(unsigned w) { return __uint_as_float(w << 16); }
; __device__ __forceinline__ float bf_hi(unsigned w) { return __uint_as_float(w & 0xffff0000u); }
; __device__ void gla_pass2(const Params& p, int l, const bf16_t* proj, bf16_t* ycat, LAS unsigned char* lds) {
;     ...
;         __syncthreads();
;         const f32x2 gg = *(const f32x2*)(p.gng + l * 512 + h * 128 + lane * 2);
;         for (int j0 = 0; j0 < 32; j0 += 8) {
;             f32x2 of[8], ob[8]; unsigned rw[8];
; #pragma unroll
;             for (int j = 0; j < 8; ++j) { const int t = seg * SEGLEN + wv * 32 + j0 + j; const size_t oo = (size_t)t * 512 + h * 128 + lane * 2;
;                 of[j] = *(const f32x2*)(OF + oo); ob[j] = *(const f32x2*)(OB + oo); rw[j] = *(const unsigned*)(proj + (size_t)t * NP + GR + h * 128 + lane * 2); }
; #pragma unroll
;             for (int j = 0; j < 8; ++j) { const int t = seg * SEGLEN + wv * 32 + j0 + j;
;                 const float o0 = of[j][0] + ob[j][0], o1 = of[j][1] + ob[j][1];
;                 const float ss = wave_sum(o0 * o0 + o1 * o1);
;                 const float rs = rsqrtf(ss * (1.0f / 128.0f) + 1e-6f);
;                 const float r0 = bf_lo(rw[j]), r1 = bf_hi(rw[j]);
;                 const float y0 = o0 * rs * gg[0] * (r0 / (1.0f + __expf(-r0))), y1 = o1 * rs * gg[1] * (r1 / (1.0f + __expf(-r1)));
;                 *(unsigned*)(ycat + (size_t)2 * SEQ * 512 + (size_t)t * 512 + h * 128 + lane * 2) = cvt_pk_bf16(y0, y1); } }
;         __syncthreads();
;     }
.LBB0_442:
	v_readlane_b32 s10, v255, 58
	s_barrier
	v_readlane_b32 s58, v255, 59
	s_add_i32 s58, s58, s59
	s_add_i32 s10, s10, s59
	s_cmpk_gt_i32 s58, 0xff
	s_barrier
	s_cbranch_scc0 .LBB0_432
	v_readlane_b32 s56, v255, 51
	v_readlane_b32 s76, v255, 43
	v_readlane_b32 s72, v255, 35
	v_readlane_b32 s66, v255, 21
	v_readlane_b32 s28, v255, 23
	v_readlane_b32 s57, v255, 52
	v_readlane_b32 s77, v255, 44
	v_readlane_b32 s78, v255, 45
	v_readlane_b32 s79, v255, 46
	v_readlane_b32 s80, v255, 47
	v_readlane_b32 s81, v255, 48
	v_readlane_b32 s82, v255, 49
	v_readlane_b32 s83, v255, 50
	v_readlane_b32 s58, v255, 57
	v_readlane_b32 s61, v255, 42
	v_readlane_b32 s73, v255, 36
	v_readlane_b32 s67, v255, 22
	v_readlane_b32 s29, v255, 24
	v_readlane_b32 s30, v255, 25
	v_readlane_b32 s64, v255, 41
	v_readlane_b32 s33, v255, 27
	v_readlane_b32 s68, v255, 28
	v_readlane_b32 s62, v255, 40
	v_readlane_b32 s69, v255, 29
	v_readlane_b32 s84, v255, 30
	v_readlane_b32 s85, v255, 39
	v_readlane_b32 s34, v255, 31
	v_readlane_b32 s35, v255, 32
	v_readlane_b32 s36, v255, 33
	v_readlane_b32 s37, v255, 34
	v_readlane_b32 s26, v255, 53
	v_readlane_b32 s31, v255, 26
	v_readlane_b32 s27, v255, 54
